# gurot
# speedup vs baseline: 1.0206x; 1.0003x over previous
.LBB0_431:
	s_ashr_i32 s43, s42, 31
	s_lshl_b64 s[44:45], s[42:43], 20
	v_readlane_b32 s6, v254, 61
	s_add_u32 s44, s6, s44
	v_readlane_b32 s6, v254, 62
	s_addc_u32 s45, s6, s45
	s_and_b64 s[46:47], s[38:39], exec
	s_cselect_b32 s6, s45, s53
	s_cselect_b32 s14, s44, s52
	s_ashr_i32 s41, s40, 31
	s_lshl_b64 s[46:47], s[40:41], 20
	s_add_u32 s46, s5, s46
	s_addc_u32 s47, s63, s47
	s_and_b64 s[60:61], s[38:39], exec
	s_cselect_b32 s17, s47, s51
	s_cselect_b32 s41, s46, s50
	s_add_u32 s43, s50, 0x100
	s_addc_u32 s49, s51, 0
	s_add_u32 s50, s52, 0x80080
	v_mov_b32_e32 v2, 0
	s_addc_u32 s51, s53, 0
	s_mov_b32 s73, -2
	v_mov_b32_e32 v3, v2
	v_mov_b32_e32 v4, v2
	v_mov_b32_e32 v5, v2
	v_mov_b32_e32 v10, v2
	v_mov_b32_e32 v11, v2
	v_mov_b32_e32 v12, v2
	v_mov_b32_e32 v13, v2
	v_mov_b32_e32 v18, v2
	v_mov_b32_e32 v19, v2
	v_mov_b32_e32 v20, v2
	v_mov_b32_e32 v21, v2
	v_mov_b32_e32 v26, v2
	v_mov_b32_e32 v27, v2
	v_mov_b32_e32 v28, v2
	v_mov_b32_e32 v29, v2
	v_mov_b32_e32 v34, v2
	v_mov_b32_e32 v35, v2
	v_mov_b32_e32 v36, v2
	v_mov_b32_e32 v37, v2
	v_mov_b32_e32 v42, v2
	v_mov_b32_e32 v43, v2
	v_mov_b32_e32 v44, v2
	v_mov_b32_e32 v45, v2
	v_mov_b32_e32 v50, v2
	v_mov_b32_e32 v51, v2
	v_mov_b32_e32 v52, v2
	v_mov_b32_e32 v53, v2
	v_mov_b32_e32 v58, v2
	v_mov_b32_e32 v59, v2
	v_mov_b32_e32 v60, v2
	v_mov_b32_e32 v61, v2
	v_mov_b32_e32 v6, v2
	v_mov_b32_e32 v7, v2
	v_mov_b32_e32 v8, v2
	v_mov_b32_e32 v9, v2
	v_mov_b32_e32 v14, v2
	v_mov_b32_e32 v15, v2
	v_mov_b32_e32 v16, v2
	v_mov_b32_e32 v17, v2
	v_mov_b32_e32 v22, v2
	v_mov_b32_e32 v23, v2
	v_mov_b32_e32 v24, v2
	v_mov_b32_e32 v25, v2
	v_mov_b32_e32 v30, v2
	v_mov_b32_e32 v31, v2
	v_mov_b32_e32 v32, v2
	v_mov_b32_e32 v33, v2
	v_mov_b32_e32 v38, v2
	v_mov_b32_e32 v39, v2
	v_mov_b32_e32 v40, v2
	v_mov_b32_e32 v41, v2
	v_mov_b32_e32 v46, v2
	v_mov_b32_e32 v47, v2
	v_mov_b32_e32 v48, v2
	v_mov_b32_e32 v49, v2
	v_mov_b32_e32 v54, v2
	v_mov_b32_e32 v55, v2
	v_mov_b32_e32 v56, v2
	v_mov_b32_e32 v57, v2
	v_mov_b32_e32 v62, v2
	v_mov_b32_e32 v63, v2
	v_mov_b32_e32 v64, v2
	v_mov_b32_e32 v65, v2
	v_mov_b32_e32 v66, v2
	v_mov_b32_e32 v67, v2
	v_mov_b32_e32 v68, v2
	v_mov_b32_e32 v69, v2
	v_mov_b32_e32 v74, v2
	v_mov_b32_e32 v75, v2
	v_mov_b32_e32 v76, v2
	v_mov_b32_e32 v77, v2
	v_mov_b32_e32 v82, v2
	v_mov_b32_e32 v83, v2
	v_mov_b32_e32 v84, v2
	v_mov_b32_e32 v85, v2
	v_mov_b32_e32 v90, v2
	v_mov_b32_e32 v91, v2
	v_mov_b32_e32 v92, v2
	v_mov_b32_e32 v93, v2
	v_mov_b32_e32 v98, v2
	v_mov_b32_e32 v99, v2
	v_mov_b32_e32 v100, v2
	v_mov_b32_e32 v101, v2
	v_mov_b32_e32 v106, v2
	v_mov_b32_e32 v107, v2
	v_mov_b32_e32 v108, v2
	v_mov_b32_e32 v109, v2
	v_mov_b32_e32 v114, v2
	v_mov_b32_e32 v115, v2
	v_mov_b32_e32 v116, v2
	v_mov_b32_e32 v117, v2
	v_mov_b32_e32 v122, v2
	v_mov_b32_e32 v123, v2
	v_mov_b32_e32 v124, v2
	v_mov_b32_e32 v125, v2
	v_mov_b32_e32 v70, v2
	v_mov_b32_e32 v71, v2
	v_mov_b32_e32 v72, v2
	v_mov_b32_e32 v73, v2
	v_mov_b32_e32 v78, v2
	v_mov_b32_e32 v79, v2
	v_mov_b32_e32 v80, v2
	v_mov_b32_e32 v81, v2
	v_mov_b32_e32 v86, v2
	v_mov_b32_e32 v87, v2
	v_mov_b32_e32 v88, v2
	v_mov_b32_e32 v89, v2
	v_mov_b32_e32 v94, v2
	v_mov_b32_e32 v95, v2
	v_mov_b32_e32 v96, v2
	v_mov_b32_e32 v97, v2
	v_mov_b32_e32 v102, v2
	v_mov_b32_e32 v103, v2
	v_mov_b32_e32 v104, v2
	v_mov_b32_e32 v105, v2
	v_mov_b32_e32 v110, v2
	v_mov_b32_e32 v111, v2
	v_mov_b32_e32 v112, v2
	v_mov_b32_e32 v113, v2
	v_mov_b32_e32 v118, v2
	v_mov_b32_e32 v119, v2
	v_mov_b32_e32 v120, v2
	v_mov_b32_e32 v121, v2
	v_mov_b32_e32 v126, v2
	v_mov_b32_e32 v127, v2
	v_mov_b32_e32 v128, v2
	v_mov_b32_e32 v129, v2
	s_add_u32 s52, s50, 0xfff80080
	s_addc_u32 s53, s51, -1
	s_cmp_eq_u32 s73, 28
	s_cselect_b32 s61, s6, s53
	s_cselect_b32 s60, s14, s52
	s_cselect_b32 s53, s17, s49
	s_cselect_b32 s52, s41, s43
.LBB0_432:
	s_add_i32 s76, 0, 0x10000
	v_add_u32_e32 v142, s76, v145
	s_add_i32 s78, 0, 0x14000
	ds_read_b128 v[154:157], v142
	ds_read_b128 v[158:161], v142 offset:1024
	ds_read_b128 v[162:165], v142 offset:2048
	ds_read_b128 v[176:179], v142 offset:3072
	v_add_u32_e32 v142, s78, v145
	ds_read_b128 v[180:183], v142
	ds_read_b128 v[184:187], v142 offset:1024
	ds_read_b128 v[188:191], v142 offset:2048
	ds_read_b128 v[192:195], v142 offset:3072
	v_lshl_add_u64 v[142:143], s[50:51], 0, v[140:141]
	s_add_i32 m0, s66, 0xc000
	ds_read_b128 v[196:199], v153
	ds_read_b128 v[200:203], v153 offset:1024
	ds_read_b128 v[204:207], v153 offset:2048
	ds_read_b128 v[208:211], v153 offset:3072
	ds_read_b128 v[224:227], v153 offset:4096
	ds_read_b128 v[228:231], v153 offset:5120
	ds_read_b128 v[232:235], v153 offset:6144
	ds_read_b128 v[236:239], v153 offset:7168
	global_load_lds_dwordx4 v[142:143], off
	v_lshl_add_u64 v[142:143], s[50:51], 0, v[138:139]
	s_add_i32 m0, s66, 0xe000
	s_nop 0
	global_load_lds_dwordx4 v[142:143], off
	s_waitcnt vmcnt(8)
	s_waitcnt lgkmcnt(0)
	s_barrier
	s_setprio 1
	s_waitcnt lgkmcnt(0)
	v_mfma_f32_16x16x32_bf16 v[126:129], v[154:157], v[196:199], v[126:129]
	v_mfma_f32_16x16x32_bf16 v[118:121], v[162:165], v[196:199], v[118:121]
	v_mfma_f32_16x16x32_bf16 v[110:113], v[154:157], v[204:207], v[110:113]
	v_mfma_f32_16x16x32_bf16 v[102:105], v[162:165], v[204:207], v[102:105]
	v_mfma_f32_16x16x32_bf16 v[94:97], v[154:157], v[224:227], v[94:97]
	v_mfma_f32_16x16x32_bf16 v[86:89], v[162:165], v[224:227], v[86:89]
	v_mfma_f32_16x16x32_bf16 v[78:81], v[154:157], v[232:235], v[78:81]
	v_mfma_f32_16x16x32_bf16 v[70:73], v[162:165], v[232:235], v[70:73]
	v_mfma_f32_16x16x32_bf16 v[126:129], v[158:161], v[200:203], v[126:129]
	v_mfma_f32_16x16x32_bf16 v[118:121], v[176:179], v[200:203], v[118:121]
	v_mfma_f32_16x16x32_bf16 v[110:113], v[158:161], v[208:211], v[110:113]
	v_mfma_f32_16x16x32_bf16 v[102:105], v[176:179], v[208:211], v[102:105]
	v_mfma_f32_16x16x32_bf16 v[94:97], v[158:161], v[228:231], v[94:97]
	v_mfma_f32_16x16x32_bf16 v[86:89], v[176:179], v[228:231], v[86:89]
	v_mfma_f32_16x16x32_bf16 v[78:81], v[158:161], v[236:239], v[78:81]
	v_mfma_f32_16x16x32_bf16 v[70:73], v[176:179], v[236:239], v[70:73]
	s_setprio 0
	s_setprio 1
	v_mfma_f32_16x16x32_bf16 v[122:125], v[180:183], v[196:199], v[122:125]
	v_mfma_f32_16x16x32_bf16 v[114:117], v[188:191], v[196:199], v[114:117]
	v_mfma_f32_16x16x32_bf16 v[106:109], v[180:183], v[204:207], v[106:109]
	v_mfma_f32_16x16x32_bf16 v[98:101], v[188:191], v[204:207], v[98:101]
	v_mfma_f32_16x16x32_bf16 v[90:93], v[180:183], v[224:227], v[90:93]
	v_mfma_f32_16x16x32_bf16 v[82:85], v[188:191], v[224:227], v[82:85]
	v_mfma_f32_16x16x32_bf16 v[74:77], v[180:183], v[232:235], v[74:77]
	v_mfma_f32_16x16x32_bf16 v[66:69], v[188:191], v[232:235], v[66:69]
	v_mfma_f32_16x16x32_bf16 v[122:125], v[184:187], v[200:203], v[122:125]
	v_mfma_f32_16x16x32_bf16 v[114:117], v[192:195], v[200:203], v[114:117]
	v_mfma_f32_16x16x32_bf16 v[106:109], v[184:187], v[208:211], v[106:109]
	v_mfma_f32_16x16x32_bf16 v[98:101], v[192:195], v[208:211], v[98:101]
	v_mfma_f32_16x16x32_bf16 v[90:93], v[184:187], v[228:231], v[90:93]
	v_mfma_f32_16x16x32_bf16 v[82:85], v[192:195], v[228:231], v[82:85]
	v_mfma_f32_16x16x32_bf16 v[74:77], v[184:187], v[236:239], v[74:77]
	v_mfma_f32_16x16x32_bf16 v[66:69], v[192:195], v[236:239], v[66:69]
	s_setprio 0
	s_barrier
	s_add_i32 s76, s76, s64
	v_lshl_add_u64 v[142:143], s[52:53], 0, v[134:135]
	s_mov_b32 m0, s76
	ds_read_b128 v[196:199], v153 offset:16384
	ds_read_b128 v[200:203], v153 offset:17408
	ds_read_b128 v[204:207], v153 offset:18432
	ds_read_b128 v[208:211], v153 offset:19456
	ds_read_b128 v[224:227], v153 offset:20480
	ds_read_b128 v[228:231], v153 offset:21504
	ds_read_b128 v[232:235], v153 offset:22528
	ds_read_b128 v[236:239], v153 offset:23552
	global_load_lds_dwordx4 v[142:143], off
	s_add_i32 m0, s76, 0x2000
	s_add_u32 s76, s52, 0x80000
	v_lshl_add_u64 v[168:169], s[52:53], 0, v[130:131]
	s_addc_u32 s77, s53, 0
	s_add_i32 s78, s78, s64
	global_load_lds_dwordx4 v[168:169], off
	v_lshl_add_u64 v[212:213], s[76:77], 0, v[134:135]
	s_mov_b32 m0, s78
	v_lshl_add_u64 v[244:245], s[60:61], 0, v[132:133]
	global_load_lds_dwordx4 v[212:213], off
	v_lshl_add_u64 v[212:213], s[76:77], 0, v[130:131]
	s_add_i32 m0, s78, 0x2000
	s_nop 0
	global_load_lds_dwordx4 v[212:213], off
	v_lshl_add_u64 v[212:213], s[60:61], 0, v[136:137]
	s_mov_b32 m0, s66
	s_nop 0
	global_load_lds_dwordx4 v[212:213], off
	s_mov_b32 m0, s67
	s_nop 0
	global_load_lds_dwordx4 v[244:245], off
	s_waitcnt vmcnt(8)
	s_waitcnt lgkmcnt(0)
	s_barrier
	s_setprio 1
	s_waitcnt lgkmcnt(0)
	v_mfma_f32_16x16x32_bf16 v[62:65], v[154:157], v[196:199], v[62:65]
	v_mfma_f32_16x16x32_bf16 v[54:57], v[162:165], v[196:199], v[54:57]
	v_mfma_f32_16x16x32_bf16 v[46:49], v[154:157], v[204:207], v[46:49]
	v_mfma_f32_16x16x32_bf16 v[38:41], v[162:165], v[204:207], v[38:41]
	v_mfma_f32_16x16x32_bf16 v[30:33], v[154:157], v[224:227], v[30:33]
	v_mfma_f32_16x16x32_bf16 v[22:25], v[162:165], v[224:227], v[22:25]
	v_mfma_f32_16x16x32_bf16 v[14:17], v[154:157], v[232:235], v[14:17]
	v_mfma_f32_16x16x32_bf16 v[6:9], v[162:165], v[232:235], v[6:9]
	v_mfma_f32_16x16x32_bf16 v[62:65], v[158:161], v[200:203], v[62:65]
	v_mfma_f32_16x16x32_bf16 v[54:57], v[176:179], v[200:203], v[54:57]
	v_mfma_f32_16x16x32_bf16 v[46:49], v[158:161], v[208:211], v[46:49]
	v_mfma_f32_16x16x32_bf16 v[38:41], v[176:179], v[208:211], v[38:41]
	v_mfma_f32_16x16x32_bf16 v[30:33], v[158:161], v[228:231], v[30:33]
	v_mfma_f32_16x16x32_bf16 v[22:25], v[176:179], v[228:231], v[22:25]
	v_mfma_f32_16x16x32_bf16 v[14:17], v[158:161], v[236:239], v[14:17]
	v_mfma_f32_16x16x32_bf16 v[6:9], v[176:179], v[236:239], v[6:9]
	s_setprio 0
	s_setprio 1
	v_mfma_f32_16x16x32_bf16 v[58:61], v[180:183], v[196:199], v[58:61]
	v_mfma_f32_16x16x32_bf16 v[50:53], v[188:191], v[196:199], v[50:53]
	v_mfma_f32_16x16x32_bf16 v[42:45], v[180:183], v[204:207], v[42:45]
	v_mfma_f32_16x16x32_bf16 v[34:37], v[188:191], v[204:207], v[34:37]
	v_mfma_f32_16x16x32_bf16 v[26:29], v[180:183], v[224:227], v[26:29]
	v_mfma_f32_16x16x32_bf16 v[18:21], v[188:191], v[224:227], v[18:21]
	v_mfma_f32_16x16x32_bf16 v[10:13], v[180:183], v[232:235], v[10:13]
	v_mfma_f32_16x16x32_bf16 v[2:5], v[188:191], v[232:235], v[2:5]
	v_mfma_f32_16x16x32_bf16 v[58:61], v[184:187], v[200:203], v[58:61]
	v_mfma_f32_16x16x32_bf16 v[50:53], v[192:195], v[200:203], v[50:53]
	v_mfma_f32_16x16x32_bf16 v[42:45], v[184:187], v[208:211], v[42:45]
	v_mfma_f32_16x16x32_bf16 v[34:37], v[192:195], v[208:211], v[34:37]
	v_mfma_f32_16x16x32_bf16 v[26:29], v[184:187], v[228:231], v[26:29]
	v_mfma_f32_16x16x32_bf16 v[18:21], v[192:195], v[228:231], v[18:21]
	v_mfma_f32_16x16x32_bf16 v[10:13], v[184:187], v[236:239], v[10:13]
	v_mfma_f32_16x16x32_bf16 v[2:5], v[192:195], v[236:239], v[2:5]
	s_setprio 0
	s_barrier
	s_add_i32 s76, 0, 0x18000
	v_add_u32_e32 v170, s76, v145
	s_add_i32 s77, 0, 0x1c000
	ds_read_b128 v[154:157], v170
	ds_read_b128 v[158:161], v170 offset:1024
	ds_read_b128 v[162:165], v170 offset:2048
	ds_read_b128 v[176:179], v170 offset:3072
	v_add_u32_e32 v170, s77, v145
	ds_read_b128 v[180:183], v170
	ds_read_b128 v[184:187], v170 offset:1024
	ds_read_b128 v[188:191], v170 offset:2048
	ds_read_b128 v[192:195], v170 offset:3072
	s_add_u32 s60, s60, 0x80000
	s_addc_u32 s61, s61, 0
	s_mov_b32 m0, s68
	v_lshl_add_u64 v[246:247], s[60:61], 0, v[136:137]
	ds_read_b128 v[196:199], v153 offset:32768
	ds_read_b128 v[200:203], v153 offset:33792
	ds_read_b128 v[204:207], v153 offset:34816
	ds_read_b128 v[208:211], v153 offset:35840
	ds_read_b128 v[224:227], v153 offset:36864
	ds_read_b128 v[228:231], v153 offset:37888
	ds_read_b128 v[232:235], v153 offset:38912
	ds_read_b128 v[236:239], v153 offset:39936
	global_load_lds_dwordx4 v[246:247], off
	v_lshl_add_u64 v[246:247], s[60:61], 0, v[132:133]
	s_mov_b32 m0, s69
	s_nop 0
	global_load_lds_dwordx4 v[246:247], off
	s_waitcnt vmcnt(8)
	s_waitcnt lgkmcnt(0)
	s_barrier
	s_setprio 1
	s_waitcnt lgkmcnt(0)
	v_mfma_f32_16x16x32_bf16 v[126:129], v[154:157], v[196:199], v[126:129]
	v_mfma_f32_16x16x32_bf16 v[118:121], v[162:165], v[196:199], v[118:121]
	v_mfma_f32_16x16x32_bf16 v[110:113], v[154:157], v[204:207], v[110:113]
	v_mfma_f32_16x16x32_bf16 v[102:105], v[162:165], v[204:207], v[102:105]
	v_mfma_f32_16x16x32_bf16 v[94:97], v[154:157], v[224:227], v[94:97]
	v_mfma_f32_16x16x32_bf16 v[86:89], v[162:165], v[224:227], v[86:89]
	v_mfma_f32_16x16x32_bf16 v[78:81], v[154:157], v[232:235], v[78:81]
	v_mfma_f32_16x16x32_bf16 v[70:73], v[162:165], v[232:235], v[70:73]
	v_mfma_f32_16x16x32_bf16 v[126:129], v[158:161], v[200:203], v[126:129]
	v_mfma_f32_16x16x32_bf16 v[118:121], v[176:179], v[200:203], v[118:121]
	v_mfma_f32_16x16x32_bf16 v[110:113], v[158:161], v[208:211], v[110:113]
	v_mfma_f32_16x16x32_bf16 v[102:105], v[176:179], v[208:211], v[102:105]
	v_mfma_f32_16x16x32_bf16 v[94:97], v[158:161], v[228:231], v[94:97]
	v_mfma_f32_16x16x32_bf16 v[86:89], v[176:179], v[228:231], v[86:89]
	v_mfma_f32_16x16x32_bf16 v[78:81], v[158:161], v[236:239], v[78:81]
	v_mfma_f32_16x16x32_bf16 v[70:73], v[176:179], v[236:239], v[70:73]
	s_setprio 0
	s_setprio 1
	v_mfma_f32_16x16x32_bf16 v[122:125], v[180:183], v[196:199], v[122:125]
	v_mfma_f32_16x16x32_bf16 v[114:117], v[188:191], v[196:199], v[114:117]
	v_mfma_f32_16x16x32_bf16 v[106:109], v[180:183], v[204:207], v[106:109]
	v_mfma_f32_16x16x32_bf16 v[98:101], v[188:191], v[204:207], v[98:101]
	v_mfma_f32_16x16x32_bf16 v[90:93], v[180:183], v[224:227], v[90:93]
	v_mfma_f32_16x16x32_bf16 v[82:85], v[188:191], v[224:227], v[82:85]
	v_mfma_f32_16x16x32_bf16 v[74:77], v[180:183], v[232:235], v[74:77]
	v_mfma_f32_16x16x32_bf16 v[66:69], v[188:191], v[232:235], v[66:69]
	v_mfma_f32_16x16x32_bf16 v[122:125], v[184:187], v[200:203], v[122:125]
	v_mfma_f32_16x16x32_bf16 v[114:117], v[192:195], v[200:203], v[114:117]
	v_mfma_f32_16x16x32_bf16 v[106:109], v[184:187], v[208:211], v[106:109]
	v_mfma_f32_16x16x32_bf16 v[98:101], v[192:195], v[208:211], v[98:101]
	v_mfma_f32_16x16x32_bf16 v[90:93], v[184:187], v[228:231], v[90:93]
	v_mfma_f32_16x16x32_bf16 v[82:85], v[192:195], v[228:231], v[82:85]
	v_mfma_f32_16x16x32_bf16 v[74:77], v[184:187], v[236:239], v[74:77]
	v_mfma_f32_16x16x32_bf16 v[66:69], v[192:195], v[236:239], v[66:69]
	s_setprio 0
	s_barrier
	s_add_i32 s60, s76, s64
	v_lshl_add_u64 v[142:143], v[142:143], 0, s[54:55]
	s_mov_b32 m0, s60
	ds_read_b128 v[196:199], v153 offset:49152
	ds_read_b128 v[200:203], v153 offset:50176
	ds_read_b128 v[204:207], v153 offset:51200
	ds_read_b128 v[208:211], v153 offset:52224
	ds_read_b128 v[224:227], v153 offset:53248
	ds_read_b128 v[228:231], v153 offset:54272
	ds_read_b128 v[232:235], v153 offset:55296
	ds_read_b128 v[236:239], v153 offset:56320
	global_load_lds_dwordx4 v[142:143], off
	s_add_i32 m0, s60, 0x2000
	s_add_u32 s52, s52, 0x80080
	v_lshl_add_u64 v[142:143], v[168:169], 0, s[54:55]
	s_addc_u32 s53, s53, 0
	s_add_i32 s60, s77, s64
	global_load_lds_dwordx4 v[142:143], off
	v_lshl_add_u64 v[142:143], s[52:53], 0, v[134:135]
	s_mov_b32 m0, s60
	s_nop 0
	global_load_lds_dwordx4 v[142:143], off
	v_lshl_add_u64 v[142:143], s[52:53], 0, v[130:131]
	s_add_i32 m0, s60, 0x2000
	s_nop 0
	global_load_lds_dwordx4 v[142:143], off
	v_lshl_add_u64 v[142:143], v[212:213], 0, s[54:55]
	s_mov_b32 m0, s70
	s_nop 0
	global_load_lds_dwordx4 v[142:143], off
	v_lshl_add_u64 v[142:143], v[244:245], 0, s[54:55]
	s_mov_b32 m0, s71
	s_nop 0
	global_load_lds_dwordx4 v[142:143], off
	s_add_i32 s73, s73, 2
	s_add_u32 s43, s43, 0x100
	s_addc_u32 s49, s49, 0
	s_add_u32 s50, s50, 0x100
	s_addc_u32 s51, s51, 0
	s_add_u32 s52, s50, 0xfff80080
	s_addc_u32 s53, s51, -1
	s_cmp_eq_u32 s73, 28
	s_cselect_b32 s61, s6, s53
	s_cselect_b32 s60, s14, s52
	s_cselect_b32 s53, s17, s49
	s_cselect_b32 s52, s41, s43
	s_waitcnt vmcnt(8)
	s_waitcnt lgkmcnt(0)
	s_barrier
	s_setprio 1
	s_waitcnt lgkmcnt(0)
	v_mfma_f32_16x16x32_bf16 v[62:65], v[154:157], v[196:199], v[62:65]
	v_mfma_f32_16x16x32_bf16 v[54:57], v[162:165], v[196:199], v[54:57]
	v_mfma_f32_16x16x32_bf16 v[46:49], v[154:157], v[204:207], v[46:49]
	v_mfma_f32_16x16x32_bf16 v[38:41], v[162:165], v[204:207], v[38:41]
	v_mfma_f32_16x16x32_bf16 v[30:33], v[154:157], v[224:227], v[30:33]
	v_mfma_f32_16x16x32_bf16 v[22:25], v[162:165], v[224:227], v[22:25]
	v_mfma_f32_16x16x32_bf16 v[14:17], v[154:157], v[232:235], v[14:17]
	v_mfma_f32_16x16x32_bf16 v[6:9], v[162:165], v[232:235], v[6:9]
	v_mfma_f32_16x16x32_bf16 v[62:65], v[158:161], v[200:203], v[62:65]
	v_mfma_f32_16x16x32_bf16 v[54:57], v[176:179], v[200:203], v[54:57]
	v_mfma_f32_16x16x32_bf16 v[46:49], v[158:161], v[208:211], v[46:49]
	v_mfma_f32_16x16x32_bf16 v[38:41], v[176:179], v[208:211], v[38:41]
	v_mfma_f32_16x16x32_bf16 v[30:33], v[158:161], v[228:231], v[30:33]
	v_mfma_f32_16x16x32_bf16 v[22:25], v[176:179], v[228:231], v[22:25]
	v_mfma_f32_16x16x32_bf16 v[14:17], v[158:161], v[236:239], v[14:17]
	v_mfma_f32_16x16x32_bf16 v[6:9], v[176:179], v[236:239], v[6:9]
	s_setprio 0
	s_setprio 1
	v_mfma_f32_16x16x32_bf16 v[58:61], v[180:183], v[196:199], v[58:61]
	v_mfma_f32_16x16x32_bf16 v[50:53], v[188:191], v[196:199], v[50:53]
	v_mfma_f32_16x16x32_bf16 v[42:45], v[180:183], v[204:207], v[42:45]
	v_mfma_f32_16x16x32_bf16 v[34:37], v[188:191], v[204:207], v[34:37]
	v_mfma_f32_16x16x32_bf16 v[26:29], v[180:183], v[224:227], v[26:29]
	v_mfma_f32_16x16x32_bf16 v[18:21], v[188:191], v[224:227], v[18:21]
	v_mfma_f32_16x16x32_bf16 v[10:13], v[180:183], v[232:235], v[10:13]
	v_mfma_f32_16x16x32_bf16 v[2:5], v[188:191], v[232:235], v[2:5]
	v_mfma_f32_16x16x32_bf16 v[58:61], v[184:187], v[200:203], v[58:61]
	v_mfma_f32_16x16x32_bf16 v[50:53], v[192:195], v[200:203], v[50:53]
	v_mfma_f32_16x16x32_bf16 v[42:45], v[184:187], v[208:211], v[42:45]
	v_mfma_f32_16x16x32_bf16 v[34:37], v[192:195], v[208:211], v[34:37]
	v_mfma_f32_16x16x32_bf16 v[26:29], v[184:187], v[228:231], v[26:29]
	v_mfma_f32_16x16x32_bf16 v[18:21], v[192:195], v[228:231], v[18:21]
	v_mfma_f32_16x16x32_bf16 v[10:13], v[184:187], v[236:239], v[10:13]
	v_mfma_f32_16x16x32_bf16 v[2:5], v[192:195], v[236:239], v[2:5]
	s_setprio 0
	s_barrier
	s_cmp_gt_u32 s73, 29
	s_cbranch_scc0 .LBB0_432
	s_and_b64 vcc, exec, s[24:25]
	s_cbranch_vccz .LBB0_435
	s_barrier
